# GEMM tile start zeroes the accumulators with 64 v_mov_b64 instead of 128 v_mov_b32; dropped inline-asm s_nop pads in the window row-sum section
# speedup vs baseline: 1.0248x; 1.0005x over previous
.LBB0_175:
	s_ashr_i32 s31, s30, 31
	s_lshl_b64 s[24:25], s[30:31], 19
	s_add_u32 s34, s62, s24
	s_addc_u32 s35, s63, s25
	s_and_b64 s[24:25], s[8:9], exec
	s_cselect_b32 s7, s35, s15
	s_cselect_b32 s11, s34, s14
	s_ashr_i32 s29, s28, 31
	s_lshl_b64 s[24:25], s[28:29], 19
	v_readlane_b32 s13, v255, 7
	s_add_u32 s96, s13, s24
	v_readlane_b32 s13, v255, 8
	s_addc_u32 s97, s13, s25
	s_and_b64 s[24:25], s[8:9], exec
	s_cselect_b32 s13, s97, s3
	s_cselect_b32 s29, s96, s2
	s_add_u32 s14, s14, 0x40080
	s_addc_u32 s15, s15, 0
	s_add_u32 s31, s2, 0x100
	s_addc_u32 s33, s3, 0
	s_mov_b32 s46, -2
	v_mov_b64_e32 v[2:3], 0
	v_mov_b64_e32 v[4:5], 0
	v_mov_b64_e32 v[6:7], 0
	v_mov_b64_e32 v[8:9], 0
	v_mov_b64_e32 v[10:11], 0
	v_mov_b64_e32 v[12:13], 0
	v_mov_b64_e32 v[14:15], 0
	v_mov_b64_e32 v[16:17], 0
	v_mov_b64_e32 v[18:19], 0
	v_mov_b64_e32 v[20:21], 0
	v_mov_b64_e32 v[22:23], 0
	v_mov_b64_e32 v[24:25], 0
	v_mov_b64_e32 v[26:27], 0
	v_mov_b64_e32 v[28:29], 0
	v_mov_b64_e32 v[30:31], 0
	v_mov_b64_e32 v[32:33], 0
	v_mov_b64_e32 v[34:35], 0
	v_mov_b64_e32 v[36:37], 0
	v_mov_b64_e32 v[38:39], 0
	v_mov_b64_e32 v[40:41], 0
	v_mov_b64_e32 v[42:43], 0
	v_mov_b64_e32 v[44:45], 0
	v_mov_b64_e32 v[46:47], 0
	v_mov_b64_e32 v[48:49], 0
	v_mov_b64_e32 v[66:67], 0
	v_mov_b64_e32 v[68:69], 0
	v_mov_b64_e32 v[70:71], 0
	v_mov_b64_e32 v[72:73], 0
	v_mov_b64_e32 v[74:75], 0
	v_mov_b64_e32 v[76:77], 0
	v_mov_b64_e32 v[78:79], 0
	v_mov_b64_e32 v[80:81], 0
	v_mov_b64_e32 v[82:83], 0
	v_mov_b64_e32 v[84:85], 0
	v_mov_b64_e32 v[86:87], 0
	v_mov_b64_e32 v[88:89], 0
	v_mov_b64_e32 v[90:91], 0
	v_mov_b64_e32 v[92:93], 0
	v_mov_b64_e32 v[94:95], 0
	v_mov_b64_e32 v[96:97], 0
	v_mov_b64_e32 v[98:99], 0
	v_mov_b64_e32 v[100:101], 0
	v_mov_b64_e32 v[102:103], 0
	v_mov_b64_e32 v[104:105], 0
	v_mov_b64_e32 v[106:107], 0
	v_mov_b64_e32 v[108:109], 0
	v_mov_b64_e32 v[110:111], 0
	v_mov_b64_e32 v[112:113], 0
	v_mov_b64_e32 v[114:115], 0
	v_mov_b64_e32 v[116:117], 0
	v_mov_b64_e32 v[118:119], 0
	v_mov_b64_e32 v[120:121], 0
	v_mov_b64_e32 v[122:123], 0
	v_mov_b64_e32 v[124:125], 0
	v_mov_b64_e32 v[126:127], 0
	v_mov_b64_e32 v[128:129], 0
	v_mov_b64_e32 v[130:131], 0
	v_mov_b64_e32 v[132:133], 0
	v_mov_b64_e32 v[134:135], 0
	v_mov_b64_e32 v[136:137], 0
	v_mov_b64_e32 v[138:139], 0
	v_mov_b64_e32 v[140:141], 0
	v_mov_b64_e32 v[142:143], 0
	v_mov_b64_e32 v[144:145], 0

.LBB0_513:
	v_add3_u32 v30, s30, v196, v0
	ds_read_b128 v[14:17], v30
	ds_read_b128 v[18:21], v30 offset:32
	v_add3_u32 v148, s29, v196, v0
	s_cmp_ge_i32 s22, s27
	s_waitcnt lgkmcnt(1)
	v_mfma_f32_32x32x16_bf16 v[48:63], v[14:17], v[2:5], 0
	ds_read_b128 v[14:17], v30 offset:4608
	ds_read_b128 v[22:25], v30 offset:4640
	ds_read_b128 v[26:29], v30 offset:64
	ds_read_b128 v[32:35], v30 offset:96
	ds_read_b128 v[36:39], v30 offset:4672
	ds_read_b128 v[144:147], v30 offset:4704
	ds_read_b128 v[44:47], v148 offset:18432
	ds_read_b128 v[40:43], v148 offset:18464
	s_waitcnt lgkmcnt(7)
	v_mfma_f32_32x32x16_bf16 v[64:79], v[14:17], v[2:5], 0
	v_add_f32_e32 v14, v1, v128
	v_add_f32_e32 v15, v1, v129
	v_add_f32_e32 v14, v14, v130
	v_add_f32_e32 v15, v15, v131
	v_add_f32_e32 v14, v14, v132
	v_mfma_f32_32x32x16_bf16 v[48:63], v[18:21], v[6:9], v[48:63]
	v_add_f32_e32 v14, v14, v134
	v_add_f32_e32 v15, v15, v133
	v_add_f32_e32 v14, v14, v136
	v_add_f32_e32 v15, v15, v135
	v_add_f32_e32 v14, v14, v138
	s_waitcnt lgkmcnt(6)
	v_mfma_f32_32x32x16_bf16 v[64:79], v[22:25], v[6:9], v[64:79]
	v_add_f32_e32 v14, v14, v140
	v_add_f32_e32 v15, v15, v137
	v_add_f32_e32 v14, v14, v142
	v_add_f32_e32 v15, v15, v139
	v_add_f32_e32 v14, v14, v80
	v_add_f32_e32 v15, v15, v141
	s_waitcnt lgkmcnt(5)
	v_mfma_f32_32x32x16_bf16 v[48:63], v[26:29], v[10:13], v[48:63]
	v_add_f32_e32 v14, v14, v82
	v_add_f32_e32 v15, v15, v143
	v_add_f32_e32 v14, v14, v84
	v_add_f32_e32 v15, v15, v81
	v_add_f32_e32 v14, v14, v86
	s_waitcnt lgkmcnt(3)
	v_mfma_f32_32x32x16_bf16 v[64:79], v[36:39], v[10:13], v[64:79]
	v_add_f32_e32 v14, v14, v88
	v_add_f32_e32 v15, v15, v83
	v_add_f32_e32 v14, v14, v90
	v_add_f32_e32 v15, v15, v85
	v_add_f32_e32 v14, v14, v92
	v_add_f32_e32 v15, v15, v87
	v_mfma_f32_32x32x16_bf16 v[48:63], v[32:35], v[176:179], v[48:63]
	v_add_f32_e32 v30, v14, v94
	v_add_f32_e32 v14, v15, v89
	v_add_f32_e32 v14, v14, v91
	v_add_f32_e32 v14, v14, v93
	v_add_f32_e32 v31, v14, v95
	ds_read_b128 v[36:39], v148 offset:23040
	ds_read_b128 v[22:25], v148 offset:23072
	ds_read_b128 v[26:29], v148 offset:18496
	ds_read_b128 v[14:17], v148 offset:18528
	ds_read_b128 v[18:21], v148 offset:23104
	ds_read_b128 v[32:35], v148 offset:23136
	s_waitcnt lgkmcnt(8)
	v_mfma_f32_32x32x16_bf16 v[64:79], v[144:147], v[176:179], v[64:79]
	s_cbranch_scc1 .LBB0_516
	s_cmp_lt_i32 s7, s19
	s_cselect_b64 s[2:3], -1, 0
	s_cmp_gt_i32 s7, s20
	s_cselect_b64 s[4:5], -1, 0
	s_or_b64 s[2:3], s[2:3], s[4:5]
	s_andn2_b64 vcc, exec, s[2:3]
	s_cbranch_vccnz .LBB0_516
	v_add_u32_e32 v144, 0x13c, v197
	s_movk_i32 s2, 0x101
	v_cmp_gt_u32_e32 vcc, s2, v144
	v_add_u32_e32 v144, 27, v197
	s_movk_i32 s3, 0xfefe
	v_cndmask_b32_e32 v48, v216, v48, vcc
	v_cmp_lt_u32_e32 vcc, s3, v144
	v_add_u32_e32 v144, 0x13b, v197
	s_nop 0
	v_cndmask_b32_e32 v64, v216, v64, vcc
	v_cmp_gt_u32_e32 vcc, s2, v144
	v_add_u32_e32 v144, 26, v197
	s_nop 0
	v_cndmask_b32_e32 v49, v216, v49, vcc
	v_cmp_lt_u32_e32 vcc, s3, v144
	v_add_u32_e32 v144, 0x13a, v197
	s_nop 0
	v_cndmask_b32_e32 v65, v216, v65, vcc
	v_cmp_gt_u32_e32 vcc, s2, v144
	v_add_u32_e32 v144, 25, v197
	s_nop 0
	v_cndmask_b32_e32 v50, v216, v50, vcc
	v_cmp_lt_u32_e32 vcc, s3, v144
	v_add_u32_e32 v144, 0x139, v197
	s_nop 0
	v_cndmask_b32_e32 v66, v216, v66, vcc
	v_cmp_gt_u32_e32 vcc, s2, v144
	v_add_u32_e32 v144, 24, v197
	s_nop 0
	v_cndmask_b32_e32 v51, v216, v51, vcc
	v_cmp_lt_u32_e32 vcc, s3, v144
	v_add_u32_e32 v144, 0x134, v197
	s_nop 0
	v_cndmask_b32_e32 v67, v216, v67, vcc
	v_cmp_gt_u32_e32 vcc, s2, v144
	v_add_u32_e32 v144, 19, v197
	s_nop 0
	v_cndmask_b32_e32 v52, v216, v52, vcc
	v_cmp_lt_u32_e32 vcc, s3, v144
	v_add_u32_e32 v144, 0x133, v197
	s_nop 0
	v_cndmask_b32_e32 v68, v216, v68, vcc
	v_cmp_gt_u32_e32 vcc, s2, v144
	v_add_u32_e32 v144, 18, v197
	s_nop 0
	v_cndmask_b32_e32 v53, v216, v53, vcc
	v_cmp_lt_u32_e32 vcc, s3, v144
	v_add_u32_e32 v144, 0x132, v197
	s_nop 0
	v_cndmask_b32_e32 v69, v216, v69, vcc
	v_cmp_gt_u32_e32 vcc, s2, v144
	v_add_u32_e32 v144, 17, v197
	s_nop 0
	v_cndmask_b32_e32 v54, v216, v54, vcc
	v_cmp_lt_u32_e32 vcc, s3, v144
	v_add_u32_e32 v144, 0x131, v197
	s_nop 0
	v_cndmask_b32_e32 v70, v216, v70, vcc
	v_cmp_gt_u32_e32 vcc, s2, v144
	v_add_u32_e32 v144, 16, v197
	s_nop 0
	v_cndmask_b32_e32 v55, v216, v55, vcc
	v_cmp_lt_u32_e32 vcc, s3, v144
	v_add_u32_e32 v144, 0x12c, v197
	s_nop 0
	v_cndmask_b32_e32 v71, v216, v71, vcc
	v_cmp_gt_u32_e32 vcc, s2, v144
	v_add_u32_e32 v144, 11, v197
	s_nop 0
	v_cndmask_b32_e32 v56, v216, v56, vcc
	v_cmp_lt_u32_e32 vcc, s3, v144
	v_add_u32_e32 v144, 0x12b, v197
	s_nop 0
	v_cndmask_b32_e32 v72, v216, v72, vcc
	v_cmp_gt_u32_e32 vcc, s2, v144
	v_add_u32_e32 v144, 10, v197
	s_nop 0
	v_cndmask_b32_e32 v57, v216, v57, vcc
	v_cmp_lt_u32_e32 vcc, s3, v144
	v_add_u32_e32 v144, 0x12a, v197
	s_nop 0
	v_cndmask_b32_e32 v73, v216, v73, vcc
	v_cmp_gt_u32_e32 vcc, s2, v144
	v_add_u32_e32 v144, 9, v197
	s_nop 0
	v_cndmask_b32_e32 v58, v216, v58, vcc
	v_cmp_lt_u32_e32 vcc, s3, v144
	v_add_u32_e32 v144, 0x129, v197
	s_nop 0
	v_cndmask_b32_e32 v74, v216, v74, vcc
	v_cmp_gt_u32_e32 vcc, s2, v144
	v_add_u32_e32 v144, 8, v197
	s_nop 0
	v_cndmask_b32_e32 v59, v216, v59, vcc
	v_cmp_lt_u32_e32 vcc, s3, v144
	v_add_u32_e32 v144, 0x124, v197
	s_nop 0
	v_cndmask_b32_e32 v75, v216, v75, vcc
	v_cmp_gt_u32_e32 vcc, s2, v144
	v_add_u32_e32 v144, 3, v197
	s_nop 0
	v_cndmask_b32_e32 v60, v216, v60, vcc
	v_cmp_lt_u32_e32 vcc, s3, v144
	v_add_u32_e32 v144, 0x123, v197
	s_nop 0
	v_cndmask_b32_e32 v76, v216, v76, vcc
	v_cmp_gt_u32_e32 vcc, s2, v144
	v_add_u32_e32 v144, 2, v197
	s_nop 0
	v_cndmask_b32_e32 v61, v216, v61, vcc
	v_cmp_lt_u32_e32 vcc, s3, v144
	v_add_u32_e32 v144, 0x122, v197
	s_nop 0
	v_cndmask_b32_e32 v77, v216, v77, vcc
	v_cmp_gt_u32_e32 vcc, s2, v144
	v_add_u32_e32 v144, 1, v197
	s_nop 0
	v_cndmask_b32_e32 v62, v216, v62, vcc
	v_cmp_lt_u32_e32 vcc, s3, v144
	v_add_u32_e32 v144, 0x121, v197
	s_nop 0
	v_cndmask_b32_e32 v78, v216, v78, vcc
	v_cmp_gt_u32_e32 vcc, s2, v144
	s_nop 1
	v_cndmask_b32_e32 v63, v216, v63, vcc
	v_cmp_lt_u32_e32 vcc, s3, v197
	s_nop 1
	v_cndmask_b32_e32 v79, v216, v79, vcc

.LBB0_649:
	s_ashr_i32 s17, s16, 31
	s_lshl_b64 s[18:19], s[16:17], 19
	s_add_u32 s18, s84, s18
	s_addc_u32 s19, s85, s19
	s_and_b64 s[20:21], s[8:9], exec
	s_cselect_b32 s17, s19, s5
	s_cselect_b32 s25, s18, s4
	s_ashr_i32 s15, s14, 31
	s_lshl_b64 s[20:21], s[14:15], 19
	s_add_u32 s20, s6, s20
	s_addc_u32 s21, s7, s21
	s_and_b64 s[26:27], s[8:9], exec
	s_cselect_b32 s15, s21, s3
	s_cselect_b32 s42, s20, s2
	s_add_u32 s46, s2, 0x100
	s_addc_u32 s47, s3, 0
	s_mov_b32 s48, -2
	s_waitcnt lgkmcnt(0)
	v_mov_b64_e32 v[2:3], 0
	v_mov_b64_e32 v[4:5], 0
	v_mov_b64_e32 v[6:7], 0
	v_mov_b64_e32 v[8:9], 0
	v_mov_b64_e32 v[10:11], 0
	v_mov_b64_e32 v[12:13], 0
	v_mov_b64_e32 v[14:15], 0
	v_mov_b64_e32 v[16:17], 0
	v_mov_b64_e32 v[18:19], 0
	v_mov_b64_e32 v[20:21], 0
	v_mov_b64_e32 v[22:23], 0
	v_mov_b64_e32 v[24:25], 0
	v_mov_b64_e32 v[26:27], 0
	v_mov_b64_e32 v[28:29], 0
	v_mov_b64_e32 v[30:31], 0
	v_mov_b64_e32 v[32:33], 0
	v_mov_b64_e32 v[34:35], 0
	v_mov_b64_e32 v[36:37], 0
	v_mov_b64_e32 v[38:39], 0
	v_mov_b64_e32 v[40:41], 0
	v_mov_b64_e32 v[42:43], 0
	v_mov_b64_e32 v[44:45], 0
	v_mov_b64_e32 v[46:47], 0
	v_mov_b64_e32 v[48:49], 0
	v_mov_b64_e32 v[50:51], 0
	v_mov_b64_e32 v[52:53], 0
	v_mov_b64_e32 v[54:55], 0
	v_mov_b64_e32 v[56:57], 0
	v_mov_b64_e32 v[58:59], 0
	v_mov_b64_e32 v[60:61], 0
	v_mov_b64_e32 v[62:63], 0
	v_mov_b64_e32 v[64:65], 0
	v_mov_b64_e32 v[66:67], 0
	v_mov_b64_e32 v[68:69], 0
	v_mov_b64_e32 v[70:71], 0
	v_mov_b64_e32 v[72:73], 0
	v_mov_b64_e32 v[74:75], 0
	v_mov_b64_e32 v[76:77], 0
	v_mov_b64_e32 v[78:79], 0
	v_mov_b64_e32 v[80:81], 0
	v_mov_b64_e32 v[82:83], 0
	v_mov_b64_e32 v[84:85], 0
	v_mov_b64_e32 v[86:87], 0
	v_mov_b64_e32 v[88:89], 0
	v_mov_b64_e32 v[90:91], 0
	v_mov_b64_e32 v[92:93], 0
	v_mov_b64_e32 v[94:95], 0
	v_mov_b64_e32 v[96:97], 0
	v_mov_b64_e32 v[98:99], 0
	v_mov_b64_e32 v[100:101], 0
	v_mov_b64_e32 v[102:103], 0
	v_mov_b64_e32 v[104:105], 0
	v_mov_b64_e32 v[106:107], 0
	v_mov_b64_e32 v[108:109], 0
	v_mov_b64_e32 v[110:111], 0
	v_mov_b64_e32 v[112:113], 0
	v_mov_b64_e32 v[114:115], 0
	v_mov_b64_e32 v[116:117], 0
	v_mov_b64_e32 v[118:119], 0
	v_mov_b64_e32 v[120:121], 0
	v_mov_b64_e32 v[122:123], 0
	v_mov_b64_e32 v[124:125], 0
	v_mov_b64_e32 v[126:127], 0
	v_mov_b64_e32 v[128:129], 0

.LBB0_782:
	s_ashr_i32 s17, s16, 31
	s_lshl_b64 s[18:19], s[16:17], 19
	s_add_u32 s18, s62, s18
	s_addc_u32 s19, s63, s19
	s_and_b64 s[20:21], s[0:1], exec
	s_cselect_b32 s17, s19, s5
	s_cselect_b32 s25, s18, s4
	s_ashr_i32 s15, s14, 31
	s_lshl_b64 s[20:21], s[14:15], 19
	s_add_u32 s20, s6, s20
	s_addc_u32 s21, s7, s21
	s_and_b64 s[26:27], s[0:1], exec
	s_cselect_b32 s15, s21, s3
	s_cselect_b32 s41, s20, s2
	s_add_u32 s4, s4, 0x40080
	s_addc_u32 s5, s5, 0
	s_add_u32 s42, s2, 0x100
	s_addc_u32 s46, s3, 0
	s_mov_b32 s47, -2
	v_mov_b64_e32 v[2:3], 0
	v_mov_b64_e32 v[4:5], 0
	v_mov_b64_e32 v[6:7], 0
	v_mov_b64_e32 v[8:9], 0
	v_mov_b64_e32 v[10:11], 0
	v_mov_b64_e32 v[12:13], 0
	v_mov_b64_e32 v[14:15], 0
	v_mov_b64_e32 v[16:17], 0
	v_mov_b64_e32 v[18:19], 0
	v_mov_b64_e32 v[20:21], 0
	v_mov_b64_e32 v[22:23], 0
	v_mov_b64_e32 v[24:25], 0
	v_mov_b64_e32 v[26:27], 0
	v_mov_b64_e32 v[28:29], 0
	v_mov_b64_e32 v[30:31], 0
	v_mov_b64_e32 v[32:33], 0
	v_mov_b64_e32 v[34:35], 0
	v_mov_b64_e32 v[36:37], 0
	v_mov_b64_e32 v[38:39], 0
	v_mov_b64_e32 v[40:41], 0
	v_mov_b64_e32 v[42:43], 0
	v_mov_b64_e32 v[44:45], 0
	v_mov_b64_e32 v[46:47], 0
	v_mov_b64_e32 v[48:49], 0
	v_mov_b64_e32 v[50:51], 0
	v_mov_b64_e32 v[52:53], 0
	v_mov_b64_e32 v[54:55], 0
	v_mov_b64_e32 v[56:57], 0
	v_mov_b64_e32 v[58:59], 0
	v_mov_b64_e32 v[60:61], 0
	v_mov_b64_e32 v[62:63], 0
	v_mov_b64_e32 v[64:65], 0
	v_mov_b64_e32 v[66:67], 0
	v_mov_b64_e32 v[68:69], 0
	v_mov_b64_e32 v[70:71], 0
	v_mov_b64_e32 v[72:73], 0
	v_mov_b64_e32 v[74:75], 0
	v_mov_b64_e32 v[76:77], 0
	v_mov_b64_e32 v[78:79], 0
	v_mov_b64_e32 v[80:81], 0
	v_mov_b64_e32 v[82:83], 0
	v_mov_b64_e32 v[84:85], 0
	v_mov_b64_e32 v[86:87], 0
	v_mov_b64_e32 v[88:89], 0
	v_mov_b64_e32 v[90:91], 0
	v_mov_b64_e32 v[92:93], 0
	v_mov_b64_e32 v[94:95], 0
	v_mov_b64_e32 v[96:97], 0
	v_mov_b64_e32 v[98:99], 0
	v_mov_b64_e32 v[100:101], 0
	v_mov_b64_e32 v[102:103], 0
	v_mov_b64_e32 v[104:105], 0
	v_mov_b64_e32 v[106:107], 0
	v_mov_b64_e32 v[108:109], 0
	v_mov_b64_e32 v[110:111], 0
	v_mov_b64_e32 v[112:113], 0
	v_mov_b64_e32 v[114:115], 0
	v_mov_b64_e32 v[116:117], 0
	v_mov_b64_e32 v[118:119], 0
	v_mov_b64_e32 v[120:121], 0
	v_mov_b64_e32 v[122:123], 0
	v_mov_b64_e32 v[124:125], 0
	v_mov_b64_e32 v[126:127], 0
	v_mov_b64_e32 v[128:129], 0

.LBB0_848:
	s_add_u32 s17, s2, 0x100
	s_addc_u32 s42, s3, 0
	s_mov_b32 s46, -2
	s_waitcnt lgkmcnt(0)
	v_mov_b64_e32 v[2:3], 0
	v_mov_b64_e32 v[4:5], 0
	v_mov_b64_e32 v[6:7], 0
	v_mov_b64_e32 v[8:9], 0
	v_mov_b64_e32 v[10:11], 0
	v_mov_b64_e32 v[12:13], 0
	v_mov_b64_e32 v[14:15], 0
	v_mov_b64_e32 v[16:17], 0
	v_mov_b64_e32 v[18:19], 0
	v_mov_b64_e32 v[20:21], 0
	v_mov_b64_e32 v[22:23], 0
	v_mov_b64_e32 v[24:25], 0
	v_mov_b64_e32 v[26:27], 0
	v_mov_b64_e32 v[28:29], 0
	v_mov_b64_e32 v[30:31], 0
	v_mov_b64_e32 v[32:33], 0
	v_mov_b64_e32 v[34:35], 0
	v_mov_b64_e32 v[36:37], 0
	v_mov_b64_e32 v[38:39], 0
	v_mov_b64_e32 v[40:41], 0
	v_mov_b64_e32 v[42:43], 0
	v_mov_b64_e32 v[44:45], 0
	v_mov_b64_e32 v[46:47], 0
	v_mov_b64_e32 v[48:49], 0
	v_mov_b64_e32 v[50:51], 0
	v_mov_b64_e32 v[52:53], 0
	v_mov_b64_e32 v[54:55], 0
	v_mov_b64_e32 v[56:57], 0
	v_mov_b64_e32 v[58:59], 0
	v_mov_b64_e32 v[60:61], 0
	v_mov_b64_e32 v[62:63], 0
	v_mov_b64_e32 v[64:65], 0
	v_mov_b64_e32 v[66:67], 0
	v_mov_b64_e32 v[68:69], 0
	v_mov_b64_e32 v[70:71], 0
	v_mov_b64_e32 v[72:73], 0
	v_mov_b64_e32 v[74:75], 0
	v_mov_b64_e32 v[76:77], 0
	v_mov_b64_e32 v[78:79], 0
	v_mov_b64_e32 v[80:81], 0
	v_mov_b64_e32 v[82:83], 0
	v_mov_b64_e32 v[84:85], 0
	v_mov_b64_e32 v[86:87], 0
	v_mov_b64_e32 v[88:89], 0
	v_mov_b64_e32 v[90:91], 0
	v_mov_b64_e32 v[92:93], 0
	v_mov_b64_e32 v[94:95], 0
	v_mov_b64_e32 v[96:97], 0
	v_mov_b64_e32 v[98:99], 0
	v_mov_b64_e32 v[100:101], 0
	v_mov_b64_e32 v[102:103], 0
	v_mov_b64_e32 v[104:105], 0
	v_mov_b64_e32 v[106:107], 0
	v_mov_b64_e32 v[108:109], 0
	v_mov_b64_e32 v[110:111], 0
	v_mov_b64_e32 v[112:113], 0
	v_mov_b64_e32 v[114:115], 0
	v_mov_b64_e32 v[116:117], 0
	v_mov_b64_e32 v[118:119], 0
	v_mov_b64_e32 v[120:121], 0
	v_mov_b64_e32 v[122:123], 0
	v_mov_b64_e32 v[124:125], 0
	v_mov_b64_e32 v[126:127], 0
	v_mov_b64_e32 v[128:129], 0
